# scan waves no longer raise their priority over the loader waves (s_setprio 3 -> 0)
# baseline (speedup 1.0000x reference)
; #define KP(f) ((decltype(Params::f))karg_ptr<(int)offsetof(Params, f)>())
; __device__ void phase_scan(int l, unsigned char* lds) {
;     int tid_ = threadIdx.x; asm volatile("" : "+v"(tid_));
;     const int tid = tid_, wid = tid >> 6, lane = tid & 63, G = gridDim.x;
;     const bool loader = wid >= 4;
;     if (!loader) __builtin_amdgcn_s_setprio(3);
;     ScanPtrs Q;
;     Q.z = KP(z); Q.sw = KP(xb) + (size_t)T_ALL * 512; Q.sa = KP(sc_a); Q.st_shift = KP(state_shift) + (size_t)l * NSB * DSH; Q.mu = KP(mu_shift) + (size_t)l * DSH;
;     Q.k_k = KP(k_k) + (size_t)l * 512; Q.k_a = KP(k_a) + (size_t)l * 512; Q.r_k = KP(r_k) + (size_t)l * 512; Q.decay0 = KP(decay0) + (size_t)l * 512; Q.a0 = KP(a0) + (size_t)l * 512; Q.rk = KP(rk);
;     bf16_t* ybuf = KP(xb);
;     const float* st_wkv = KP(state_wkv); float* out = KP(out);
;     int J = (G % 8 == 0) ? (int)(blockIdx.x % 8) * (G / 8) + (int)(blockIdx.x / 8) : (int)blockIdx.x, ci = 0, it = 0;
.LBB0_401:
	s_or_b64 exec, exec, s[8:9]
	s_mov_b32 s6, s46
	s_mov_b32 s7, s2
	v_mov_b32_e32 v53, v166
	s_waitcnt lgkmcnt(0)
	s_barrier
	s_nop 0
	v_ashrrev_i32_e32 v52, 6, v53
	v_cmp_lt_i32_e64 s[10:11], 3, v52
	v_cmp_gt_i32_e64 s[12:13], 4, v52
	s_and_saveexec_b64 s[8:9], s[12:13]
	s_setprio 0
	s_or_b64 exec, exec, s[8:9]
	s_load_dwordx2 s[24:25], s[0:1], 0x130
	s_waitcnt lgkmcnt(0)
	s_load_dwordx2 s[14:15], s[0:1], 0x120
	s_waitcnt lgkmcnt(0)
	s_load_dwordx2 s[26:27], s[0:1], 0x140
	s_waitcnt lgkmcnt(0)
	s_load_dwordx2 s[28:29], s[0:1], 16
	s_waitcnt lgkmcnt(0)
	s_load_dwordx2 s[30:31], s[0:1], 56
	s_waitcnt lgkmcnt(0)
	s_load_dwordx2 s[34:35], s[0:1], 0x68
	s_waitcnt lgkmcnt(0)
	s_load_dwordx2 s[36:37], s[0:1], 0x70
	s_waitcnt lgkmcnt(0)
	s_load_dwordx2 s[38:39], s[0:1], 0x78
	s_waitcnt lgkmcnt(0)
	s_load_dwordx2 s[40:41], s[0:1], 64
	s_waitcnt lgkmcnt(0)
	s_load_dwordx2 s[56:57], s[0:1], 0x50
	s_waitcnt lgkmcnt(0)
	s_load_dwordx2 s[58:59], s[0:1], 0x150
	s_waitcnt lgkmcnt(0)
	s_load_dwordx2 s[60:61], s[0:1], 0x120
	s_waitcnt lgkmcnt(0)
	s_load_dwordx2 s[22:23], s[0:1], 32
	s_waitcnt lgkmcnt(0)
	s_load_dwordx2 s[62:63], s[0:1], 0xd8
	s_waitcnt lgkmcnt(0)
	v_cndmask_b32_e64 v0, 0, 1, s[54:55]
	v_cmp_ne_u32_e64 s[6:7], 1, v0
	s_andn2_b64 vcc, exec, s[54:55]
	s_mov_b32 s51, s2
	v_writelane_b32 v230, s6, 6
	s_nop 1
	v_writelane_b32 v230, s7, 7
	s_cbranch_vccnz .LBB0_405
	s_and_b32 s6, s2, 7
	s_ashr_i32 s7, s46, 3
	s_mul_i32 s6, s7, s6
	s_lshr_b32 s7, s2, 3
	s_add_i32 s51, s6, s7

; #define KP(f) ((decltype(Params::f))karg_ptr<(int)offsetof(Params, f)>())
; __device__ void phase_scan(int l, unsigned char* lds) {
;     int tid_ = threadIdx.x; asm volatile("" : "+v"(tid_));
;     const int tid = tid_, wid = tid >> 6, lane = tid & 63, G = gridDim.x;
;     const bool loader = wid >= 4;
;     if (!loader) __builtin_amdgcn_s_setprio(3);
;     ScanPtrs Q;
;     Q.z = KP(z); Q.sw = KP(xb) + (size_t)T_ALL * 512; Q.sa = KP(sc_a); Q.st_shift = KP(state_shift) + (size_t)l * NSB * DSH; Q.mu = KP(mu_shift) + (size_t)l * DSH;
;     Q.k_k = KP(k_k) + (size_t)l * 512; Q.k_a = KP(k_a) + (size_t)l * 512; Q.r_k = KP(r_k) + (size_t)l * 512; Q.decay0 = KP(decay0) + (size_t)l * 512; Q.a0 = KP(a0) + (size_t)l * 512; Q.rk = KP(rk);
;     bf16_t* ybuf = KP(xb);
;     const float* st_wkv = KP(state_wkv); float* out = KP(out);
;     int J = (G % 8 == 0) ? (int)(blockIdx.x % 8) * (G / 8) + (int)(blockIdx.x / 8) : (int)blockIdx.x, ci = 0, it = 0;
.LBB0_1542:
	s_or_b64 exec, exec, s[10:11]
	s_mov_b32 s6, s2
	s_mov_b32 s7, s46
	v_mov_b32_e32 v53, v166
	s_waitcnt lgkmcnt(0)
	s_barrier
	s_nop 0
	v_ashrrev_i32_e32 v52, 6, v53
	v_cmp_lt_i32_e64 s[10:11], 3, v52
	v_cmp_gt_i32_e64 s[12:13], 4, v52
	s_and_saveexec_b64 s[14:15], s[12:13]
	s_setprio 0
	s_or_b64 exec, exec, s[14:15]
	s_load_dwordx2 s[22:23], s[0:1], 0x130
	s_waitcnt lgkmcnt(0)
	s_load_dwordx2 s[16:17], s[0:1], 0x120
	s_waitcnt lgkmcnt(0)
	s_load_dwordx2 s[24:25], s[0:1], 0x140
	s_waitcnt lgkmcnt(0)
	s_load_dwordx2 s[18:19], s[0:1], 16
	s_waitcnt lgkmcnt(0)
	s_load_dwordx2 s[14:15], s[0:1], 56
	s_waitcnt lgkmcnt(0)
	s_load_dwordx2 s[26:27], s[0:1], 0x68
	s_waitcnt lgkmcnt(0)
	s_load_dwordx2 s[28:29], s[0:1], 0x70
	s_waitcnt lgkmcnt(0)
	s_load_dwordx2 s[30:31], s[0:1], 0x78
	s_waitcnt lgkmcnt(0)
	s_load_dwordx2 s[34:35], s[0:1], 64
	s_waitcnt lgkmcnt(0)
	s_load_dwordx2 s[36:37], s[0:1], 0x50
	s_waitcnt lgkmcnt(0)
	s_load_dwordx2 s[38:39], s[0:1], 0x150
	s_waitcnt lgkmcnt(0)
	s_load_dwordx2 s[40:41], s[0:1], 0x120
	s_waitcnt lgkmcnt(0)
	s_load_dwordx2 s[20:21], s[0:1], 32
	s_waitcnt lgkmcnt(0)
	s_load_dwordx2 s[42:43], s[0:1], 0xd8
	s_waitcnt lgkmcnt(0)
	v_readlane_b32 s6, v230, 6
	v_readlane_b32 s7, v230, 7
	s_and_b64 vcc, exec, s[6:7]
	s_mov_b32 s53, s2
	s_cbranch_vccnz .LBB0_1546
	s_and_b32 s6, s2, 7
	s_ashr_i32 s7, s46, 3
	s_mul_i32 s6, s7, s6
	s_lshr_b32 s7, s2, 3
	s_add_i32 s53, s6, s7
